# attention NOSWAP variant (V tile in natural key order, no permlane swaps, no canonicalizing max) inside the full stack
# speedup vs baseline: 1.0094x; 1.0094x over previous
; __device__ __forceinline__ int v_rd_base(int lane) { return ((lane & 3) << 3) | (((lane >> 2) & 3) << 6) | (((lane >> 4) & 1) << 5) | (((lane >> 5) & 1) << 8); }
; #define WAITBAR(N) asm volatile("s_waitcnt vmcnt(" #N ") lgkmcnt(0)\n\ts_barrier" ::: "memory")
; __device__ __forceinline__ void attn_unit(int b, int h, int qb, const bf16_t* __restrict__ proj, const float* __restrict__ btab, float lam, float outscale,
;                                           const float* __restrict__ gain, float* o1scr, bf16_t* merged, LAS char* lds) {
;     ...
;     { const int row = wid * 8 + (lane >> 3), c16 = (lane & 7) ^ ((row >> 1) & 7); koff = (unsigned)((row * LD + c16 * 8) * 2);
;       const int within = lane & 31;
; #pragma unroll
;       for (int i = 0; i < 2; ++i) { const int sub = (2 * wid + i) * 2 + (lane >> 5); const int kk = (sub >> 2) * 8 + (within >> 2);
;           const int k = (kk & ~0xC) | ((kk & 4) << 1) | ((kk & 8) >> 1), c = (sub & 3) * 32 + (within & 3) * 8;
;           const unsigned o = (unsigned)((k * LD + c) * 2); if (i == 0) voffA = o; else voffB = o; } }
;     const int vb0 = (int)(unsigned)(uintptr_t)V_lds + v_rd_base(lane);
;     const bf16_t* Vh = proj + rowbase * LD + OV + h * 128;
; #pragma unroll 1
;     for (int s = 0; s < 2; ++s) {
;         const int hq = 2 * h + s;
;         const bf16_t* Kh = proj + rowbase * LD + OKK + hq * 64;
;         const bf16_t* Qw = proj + (rowbase + qw + r32) * LD + OQ + hq * 64 + hi * 8;
;         float m_reg = -1e30f, l_reg = 0; f32x16 o[4]; bf16x8 qr[4];
; #pragma unroll
;         for (int d0 = 0; d0 < 4; ++d0) { o[d0] = f32x16{}; qr[d0] = *(const bf16x8*)(Qw + d0 * 16); }
;     ...
;         f32x16 pA0, pA1, pB0, pB1; float mnA, mnB, alA, alB, bo; bf16x8 pa0, pa1, pa2, pa3; constexpr int NT = T / 64;
;         asm volatile("s_waitcnt vmcnt(0) lgkmcnt(0)" ::: "memory"); __syncthreads();
;         DMA_TILE(0, 0); DMA_TILE(1, 1);
;         WAITBAR(3);
;         bo = qkt(pA0, pA1, K_lds, qr, r32, hi, 0 - qw, cL, cR, tabL); partialSM(pA0, pA1, m_reg, mnA, alA, bo);
;         int bc = 1, bp = 0, bn = 2;
.LBB0_187:
	s_or_b32 s24, s6, s48
	s_lshl_b64 s[2:3], s[24:25], 1
	v_lshl_add_u64 v[2:3], v[190:191], 0, s[2:3]
	s_add_u32 s2, s36, s2
	s_addc_u32 s3, s37, s3
	global_load_dwordx4 v[142:145], v[2:3], off
	global_load_dwordx4 v[138:141], v[2:3], off offset:32
	global_load_dwordx4 v[134:137], v[2:3], off offset:64
	global_load_dwordx4 v[130:133], v[2:3], off offset:96
	v_lshl_add_u64 v[184:185], s[2:3], 0, v[186:187]
	s_xor_b64 s[2:3], s[0:1], -1
	s_mov_b64 s[6:7], 0x800
	v_lshl_add_u64 v[184:185], v[184:185], 0, s[6:7]
	v_mov_b64_e32 v[250:251], v[192:193]
	v_mov_b64_e32 v[246:247], v[194:195]
	s_mov_b32 s6, 0xc8000
	s_mov_b32 s7, 0
	v_readfirstlane_b32 s67, v222
	v_add_u32_e32 v239, v226, v227
	v_add_u32_e32 v240, v226, v228
	v_add_u32_e32 v241, v226, v229
	v_add_u32_e32 v242, v226, v230
	s_lshr_b32 s67, s67, 8
	v_add_u32_e32 v239, 0x14000, v239
	v_add_u32_e32 v240, 0x14000, v240
	v_add_u32_e32 v241, 0x14000, v241
	v_add_u32_e32 v242, 0x14000, v242
	v_mov_b32_e32 v243, v215
	v_bfe_u32 v244, v222, 4, 1
	v_bfe_u32 v249, v222, 6, 1
	v_sub_u32_e32 v244, v249, v244
	v_mul_i32_i24_e32 v244, 0xc800, v244
	v_ashrrev_i32_e32 v245, 31, v244
	v_lshl_add_u64 v[250:251], v[250:251], 0, v[244:245]
	v_lshl_add_u64 v[246:247], v[246:247], 0, v[244:245]
	v_mov_b32_e32 v2, 0
	v_mov_b32_e32 v3, 0
	v_mov_b32_e32 v4, 0
	v_mov_b32_e32 v5, 0
	v_mov_b32_e32 v6, 0
	v_mov_b32_e32 v7, 0
	v_mov_b32_e32 v8, 0
	v_mov_b32_e32 v9, 0
	v_mov_b32_e32 v10, 0
	v_mov_b32_e32 v11, 0
	v_mov_b32_e32 v12, 0
	v_mov_b32_e32 v13, 0
	v_mov_b32_e32 v14, 0
	v_mov_b32_e32 v15, 0
	v_mov_b32_e32 v16, 0
	v_mov_b32_e32 v17, 0
	v_mov_b32_e32 v18, 0
	v_mov_b32_e32 v19, 0
	v_mov_b32_e32 v20, 0
	v_mov_b32_e32 v21, 0
	v_mov_b32_e32 v22, 0
	v_mov_b32_e32 v23, 0
	v_mov_b32_e32 v24, 0
	v_mov_b32_e32 v25, 0
	v_mov_b32_e32 v26, 0
	v_mov_b32_e32 v27, 0
	v_mov_b32_e32 v28, 0
	v_mov_b32_e32 v29, 0
	v_mov_b32_e32 v30, 0
	v_mov_b32_e32 v31, 0
	v_mov_b32_e32 v32, 0
	v_mov_b32_e32 v33, 0
	v_mov_b32_e32 v34, 0
	v_mov_b32_e32 v35, 0
	v_mov_b32_e32 v36, 0
	v_mov_b32_e32 v37, 0
	v_mov_b32_e32 v38, 0
	v_mov_b32_e32 v39, 0
	v_mov_b32_e32 v40, 0
	v_mov_b32_e32 v41, 0
	v_mov_b32_e32 v42, 0
	v_mov_b32_e32 v43, 0
	v_mov_b32_e32 v44, 0
	v_mov_b32_e32 v45, 0
	v_mov_b32_e32 v46, 0
	v_mov_b32_e32 v47, 0
	v_mov_b32_e32 v48, 0
	v_mov_b32_e32 v49, 0
	v_mov_b32_e32 v50, 0
	v_mov_b32_e32 v51, 0
	v_mov_b32_e32 v52, 0
	v_mov_b32_e32 v53, 0
	v_mov_b32_e32 v54, 0
	v_mov_b32_e32 v55, 0
	v_mov_b32_e32 v56, 0
	v_mov_b32_e32 v57, 0
	v_mov_b32_e32 v58, 0
	v_mov_b32_e32 v59, 0
	v_mov_b32_e32 v60, 0
	v_mov_b32_e32 v61, 0
	v_mov_b32_e32 v62, 0
	v_mov_b32_e32 v63, 0
	v_mov_b32_e32 v64, 0
	v_mov_b32_e32 v65, 0
	v_mov_b32_e32 v238, 0
	v_add_u32_e32 v245, 0xffffff00, v235
	s_sub_i32 s65, s78, 0x80
	s_mov_b32 s40, 0
	s_waitcnt vmcnt(0) lgkmcnt(0)
	s_barrier
	s_mov_b32 s24, 0
	s_lshl_b32 s12, s24, 13
	s_add_i32 s12, s12, s66
	s_lshl_b32 s13, s24, 14
	s_add_i32 s13, s13, s74
	s_add_i32 m0, s12, 0x14000
	s_nop 0
	global_load_lds_dwordx4 v[184:185], off
	s_mov_b32 m0, s13
	v_lshl_add_u64 v[184:185], v[184:185], 0, s[6:7]
	global_load_lds_dwordx4 v[250:251], off
	s_add_i32 m0, s13, 0x400
	v_lshl_add_u64 v[250:251], v[250:251], 0, s[6:7]
	global_load_lds_dwordx4 v[246:247], off
	v_lshl_add_u64 v[246:247], v[246:247], 0, s[6:7]
	s_mov_b32 s24, 1
	s_lshl_b32 s12, s24, 13
	s_add_i32 s12, s12, s66
	s_lshl_b32 s13, s24, 14
	s_add_i32 s13, s13, s74
	s_add_i32 m0, s12, 0x14000
	s_nop 0
	global_load_lds_dwordx4 v[184:185], off
	s_mov_b32 m0, s13
	v_lshl_add_u64 v[184:185], v[184:185], 0, s[6:7]
	global_load_lds_dwordx4 v[250:251], off
	s_add_i32 m0, s13, 0x400
	v_lshl_add_u64 v[250:251], v[250:251], 0, s[6:7]
	global_load_lds_dwordx4 v[246:247], off
	v_lshl_add_u64 v[246:247], v[246:247], 0, s[6:7]
	s_waitcnt vmcnt(3)
	s_barrier
	s_cmp_eq_u32 s67, 0
	s_cbranch_scc1 .Lat_enter
	s_barrier
